# grid barrier: the last XCD leader advances every XCD's generation word itself, so other XCDs' workgroups are released in one hop instead of via their own leader; gate-path rsqrt LDS reads hoisted
# baseline (speedup 1.0000x reference)
; DI float sigmoidf_(float v) { return 1.f / (1.f + __expf(-v)); }
; DI void phaseA_tile(const P& p, int layer, int mt, int nt, char* lds) {
;     ...
;   if (seg >= 53) {
;     const bool isP = seg < 69;
;     unsigned* G = (unsigned*)(p.ws + (isP ? W_GP : W_GA)) + ((size_t)(((row0 >> 6) + wm) * 16 + (isP ? seg - 53 : seg - 69)) * 64 + lane) * 16;
; #pragma unroll
;     for (int mi = 0; mi < 4; ++mi) {
;       unsigned wv[4];
; #pragma unroll
;       for (int ni = 0; ni < 4; ++ni) {
;         unsigned w_ = 0u;
; #pragma unroll
;         for (int j = 0; j < 4; ++j) {
;           const float r = rr[wm * 64 + mi * 16 + fq * 4 + j];
;           w_ |= ((unsigned)(int)(sigmoidf_(acc[mi][ni][j] * r) * 255.f + 0.5f)) << (8 * j);
;         }
;         wv[ni] = w_;
;       }
;       *(u32x4*)(G + mi * 4) = u32x4{wv[0], wv[1], wv[2], wv[3]};
;     }
.LBB0_1584:
	s_and_b64 vcc, exec, s[0:1]
	s_cbranch_vccz .LBB0_1183
	v_lshlrev_b32_e32 v66, 2, v127
	v_lshl_add_u32 v66, s11, 2, v66
	v_add_u32_e32 v66, 0x10800, v66
	ds_read_b128 v[68:71], v66
	ds_read_b128 v[76:79], v66 offset:64
	ds_read_b128 v[80:83], v66 offset:128
	ds_read_b128 v[84:87], v66 offset:192
	s_cmpk_lt_u32 s55, 0x45
	s_cselect_b64 s[0:1], -1, 0
	s_and_b64 s[4:5], s[0:1], exec
	s_mov_b32 s4, 0x17ca2000
	s_waitcnt lgkmcnt(0)
	v_mul_f32_e32 v63, v63, v69
	v_mul_f32_e32 v63, 0xbfb8aa3b, v63
	s_cselect_b32 s4, s4, 0x19d22000
	v_exp_f32_e32 v72, v63
	v_mul_f32_e32 v63, v64, v70
	s_add_u32 s4, s90, s4
	v_mul_f32_e32 v63, 0xbfb8aa3b, v63
	s_addc_u32 s5, s91, 0
	s_lshl_b32 s10, s36, 5
	s_lshl_b32 s12, s56, 4
	v_exp_f32_e32 v64, v63
	v_mul_f32_e32 v63, v65, v71
	v_mul_f32_e32 v58, v58, v68
	s_and_b64 s[0:1], s[0:1], exec
	v_mul_f32_e32 v63, 0xbfb8aa3b, v63
	v_mul_f32_e32 v58, 0xbfb8aa3b, v58
	s_movk_i32 s0, 0xffcb
	v_mul_f32_e32 v62, v62, v68
	v_exp_f32_e32 v74, v63
	v_exp_f32_e32 v63, v58
	v_mul_f32_e32 v58, v59, v69
	s_cselect_b32 s0, s0, 0xffffffbb
	s_add_i32 s1, s12, s10
	v_mul_f32_e32 v62, 0xbfb8aa3b, v62
	v_mul_f32_e32 v58, 0xbfb8aa3b, v58
	s_add_i32 s1, s1, s55
	v_exp_f32_e32 v62, v62
	v_exp_f32_e32 v73, v58
	v_mul_f32_e32 v58, v60, v70
	s_add_i32 s0, s1, s0
	v_mul_f32_e32 v58, 0xbfb8aa3b, v58
	s_ashr_i32 s1, s0, 31
	v_exp_f32_e32 v65, v58
	v_mul_f32_e32 v58, v61, v71
	s_lshl_b64 s[0:1], s[0:1], 12
	v_mul_f32_e32 v58, 0xbfb8aa3b, v58
	s_add_u32 s0, s4, s0
	v_exp_f32_e32 v75, v58
	v_pk_add_f32 v[58:59], v[62:63], 1.0 op_sel_hi:[1,0]
	s_addc_u32 s1, s5, s1
	s_mov_b32 s10, 0x437f0000
	v_mul_f32_e32 v55, v55, v69
	v_mul_f32_e32 v55, 0xbfb8aa3b, v55
	v_rcp_f32_e32 v59, v59
	v_mul_f32_e32 v50, v50, v68
	v_mul_f32_e32 v50, 0xbfb8aa3b, v50
	v_mul_f32_e32 v54, v54, v68
	v_rcp_f32_e32 v58, v58
	s_nop 0
	v_pk_fma_f32 v[58:59], v[58:59], s[10:11], 0.5 op_sel_hi:[1,0,0]
	v_mul_f32_e32 v54, 0xbfb8aa3b, v54
	v_cvt_i32_f32_e32 v60, v59
	v_cvt_i32_f32_e32 v61, v58
	v_pk_add_f32 v[58:59], v[72:73], 1.0 op_sel_hi:[1,0]
	v_exp_f32_e32 v54, v54
	v_lshlrev_b32_e32 v0, 6, v152
	v_rcp_f32_e32 v59, v59
	v_rcp_f32_e32 v58, v58
	s_nop 0
	v_pk_fma_f32 v[58:59], v[58:59], s[10:11], 0.5 op_sel_hi:[1,0,0]
	s_nop 0
	v_cvt_i32_f32_e32 v58, v58
	v_cvt_i32_f32_e32 v59, v59
	v_lshlrev_b32_e32 v58, 8, v58
	v_lshlrev_b32_e32 v59, 8, v59
	v_or_b32_e32 v60, v59, v60
	v_or_b32_e32 v61, v58, v61
	v_pk_add_f32 v[58:59], v[64:65], 1.0 op_sel_hi:[1,0]
	s_nop 0
	v_rcp_f32_e32 v59, v59
	v_rcp_f32_e32 v58, v58
	s_nop 0
	v_pk_fma_f32 v[58:59], v[58:59], s[10:11], 0.5 op_sel_hi:[1,0,0]
	s_nop 0
	v_cvt_i32_f32_sdwa v58, v58 dst_sel:WORD_1 dst_unused:UNUSED_PAD src0_sel:DWORD
	v_cvt_i32_f32_sdwa v59, v59 dst_sel:WORD_1 dst_unused:UNUSED_PAD src0_sel:DWORD
	v_or_b32_e32 v61, v61, v58
	v_or_b32_e32 v60, v60, v59
	v_pk_add_f32 v[58:59], v[74:75], 1.0 op_sel_hi:[1,0]
	s_nop 0
	v_rcp_f32_e32 v59, v59
	v_rcp_f32_e32 v58, v58
	s_nop 0
	v_pk_fma_f32 v[58:59], v[58:59], s[10:11], 0.5 op_sel_hi:[1,0,0]
	s_nop 0
	v_cvt_i32_f32_sdwa v59, v59 dst_sel:BYTE_3 dst_unused:UNUSED_PAD src0_sel:DWORD
	v_cvt_i32_f32_sdwa v58, v58 dst_sel:BYTE_3 dst_unused:UNUSED_PAD src0_sel:DWORD
	v_or_b32_e32 v59, v60, v59
	v_exp_f32_e32 v60, v55
	v_mul_f32_e32 v55, v56, v70
	v_mul_f32_e32 v55, 0xbfb8aa3b, v55
	v_exp_f32_e32 v56, v55
	v_mul_f32_e32 v55, v57, v71
	v_mul_f32_e32 v55, 0xbfb8aa3b, v55
	v_exp_f32_e32 v62, v55
	v_exp_f32_e32 v55, v50
	v_mul_f32_e32 v50, v51, v69
	v_mul_f32_e32 v50, 0xbfb8aa3b, v50
	v_or_b32_e32 v58, v61, v58
	v_exp_f32_e32 v61, v50
	v_mul_f32_e32 v50, v52, v70
	v_mul_f32_e32 v50, 0xbfb8aa3b, v50
	v_exp_f32_e32 v57, v50
	v_mul_f32_e32 v50, v53, v71
	v_mul_f32_e32 v50, 0xbfb8aa3b, v50
	v_exp_f32_e32 v63, v50
	v_pk_add_f32 v[50:51], v[54:55], 1.0 op_sel_hi:[1,0]
	s_nop 0
	v_rcp_f32_e32 v51, v51
	v_rcp_f32_e32 v50, v50
	s_nop 0
	v_pk_fma_f32 v[50:51], v[50:51], s[10:11], 0.5 op_sel_hi:[1,0,0]
	s_nop 0
	v_cvt_i32_f32_e32 v52, v51
	v_cvt_i32_f32_e32 v53, v50
	v_pk_add_f32 v[50:51], v[60:61], 1.0 op_sel_hi:[1,0]
	s_nop 0
	v_rcp_f32_e32 v51, v51
	v_rcp_f32_e32 v50, v50
	s_nop 0
	v_pk_fma_f32 v[50:51], v[50:51], s[10:11], 0.5 op_sel_hi:[1,0,0]
	s_nop 0
	v_cvt_i32_f32_e32 v50, v50
	v_cvt_i32_f32_e32 v51, v51
	v_lshlrev_b32_e32 v50, 8, v50
	v_lshlrev_b32_e32 v51, 8, v51
	v_or_b32_e32 v52, v51, v52
	v_or_b32_e32 v53, v50, v53
	v_pk_add_f32 v[50:51], v[56:57], 1.0 op_sel_hi:[1,0]
	s_nop 0
	v_rcp_f32_e32 v51, v51
	v_rcp_f32_e32 v50, v50
	s_nop 0
	v_pk_fma_f32 v[50:51], v[50:51], s[10:11], 0.5 op_sel_hi:[1,0,0]
	s_nop 0
	v_cvt_i32_f32_sdwa v50, v50 dst_sel:WORD_1 dst_unused:UNUSED_PAD src0_sel:DWORD
	v_cvt_i32_f32_sdwa v51, v51 dst_sel:WORD_1 dst_unused:UNUSED_PAD src0_sel:DWORD
	v_or_b32_e32 v53, v53, v50
	v_or_b32_e32 v52, v52, v51
	v_pk_add_f32 v[50:51], v[62:63], 1.0 op_sel_hi:[1,0]
	s_nop 0
	v_rcp_f32_e32 v51, v51
	v_rcp_f32_e32 v50, v50
	s_nop 0
	v_pk_fma_f32 v[50:51], v[50:51], s[10:11], 0.5 op_sel_hi:[1,0,0]
	s_nop 0
	v_cvt_i32_f32_sdwa v50, v50 dst_sel:BYTE_3 dst_unused:UNUSED_PAD src0_sel:DWORD
	v_cvt_i32_f32_sdwa v51, v51 dst_sel:BYTE_3 dst_unused:UNUSED_PAD src0_sel:DWORD
	v_or_b32_e32 v60, v53, v50
	v_or_b32_e32 v61, v52, v51
	v_mov_b32_e32 v50, v76
	v_mov_b32_e32 v51, v77
	v_mov_b32_e32 v52, v78
	v_mov_b32_e32 v53, v79
	global_store_dwordx4 v0, v[58:61], s[0:1]
	s_waitcnt lgkmcnt(0)
; DI float sigmoidf_(float v) { return 1.f / (1.f + __expf(-v)); }
; DI void phaseA_tile(const P& p, int layer, int mt, int nt, char* lds) {
;     ...
;     for (int mi = 0; mi < 4; ++mi) {
;       unsigned wv[4];
; #pragma unroll
;       for (int ni = 0; ni < 4; ++ni) {
;         unsigned w_ = 0u;
; #pragma unroll
;         for (int j = 0; j < 4; ++j) {
;           const float r = rr[wm * 64 + mi * 16 + fq * 4 + j];
;           w_ |= ((unsigned)(int)(sigmoidf_(acc[mi][ni][j] * r) * 255.f + 0.5f)) << (8 * j);
;         }
;         wv[ni] = w_;
;       }
;       *(u32x4*)(G + mi * 4) = u32x4{wv[0], wv[1], wv[2], wv[3]};
	v_mul_f32_e32 v46, v46, v50
	v_mul_f32_e32 v42, v42, v50
	v_mul_f32_e32 v46, 0xbfb8aa3b, v46
	v_mul_f32_e32 v42, 0xbfb8aa3b, v42
	v_exp_f32_e32 v54, v46
	v_mul_f32_e32 v46, v47, v51
	v_exp_f32_e32 v55, v42
	v_mul_f32_e32 v42, v43, v51
	v_mul_f32_e32 v46, 0xbfb8aa3b, v46
	v_mul_f32_e32 v42, 0xbfb8aa3b, v42
	v_exp_f32_e32 v56, v46
	v_mul_f32_e32 v46, v48, v52
	v_exp_f32_e32 v57, v42
	v_mul_f32_e32 v42, v44, v52
	v_mul_f32_e32 v46, 0xbfb8aa3b, v46
	v_mul_f32_e32 v42, 0xbfb8aa3b, v42
	v_exp_f32_e32 v48, v46
	v_mul_f32_e32 v46, v49, v53
	v_exp_f32_e32 v49, v42
	v_mul_f32_e32 v42, v45, v53
	v_mul_f32_e32 v42, 0xbfb8aa3b, v42
	v_exp_f32_e32 v47, v42
	v_pk_add_f32 v[42:43], v[54:55], 1.0 op_sel_hi:[1,0]
	v_mul_f32_e32 v46, 0xbfb8aa3b, v46
	v_exp_f32_e32 v46, v46
	v_mul_f32_e32 v39, v39, v51
	v_mul_f32_e32 v39, 0xbfb8aa3b, v39
	v_rcp_f32_e32 v43, v43
	v_mul_f32_e32 v34, v34, v50
	v_mul_f32_e32 v34, 0xbfb8aa3b, v34
	v_mul_f32_e32 v38, v38, v50
	v_rcp_f32_e32 v42, v42
	s_nop 0
	v_pk_fma_f32 v[42:43], v[42:43], s[10:11], 0.5 op_sel_hi:[1,0,0]
	v_mul_f32_e32 v38, 0xbfb8aa3b, v38
	v_cvt_i32_f32_e32 v44, v43
	v_cvt_i32_f32_e32 v45, v42
	v_pk_add_f32 v[42:43], v[56:57], 1.0 op_sel_hi:[1,0]
	v_exp_f32_e32 v38, v38
	v_rcp_f32_e32 v43, v43
	v_rcp_f32_e32 v42, v42
	s_nop 0
	v_pk_fma_f32 v[42:43], v[42:43], s[10:11], 0.5 op_sel_hi:[1,0,0]
	s_nop 0
	v_cvt_i32_f32_e32 v42, v42
	v_cvt_i32_f32_e32 v43, v43
	v_lshlrev_b32_e32 v42, 8, v42
	v_lshlrev_b32_e32 v43, 8, v43
	v_or_b32_e32 v44, v43, v44
	v_or_b32_e32 v45, v42, v45
	v_pk_add_f32 v[42:43], v[48:49], 1.0 op_sel_hi:[1,0]
	s_nop 0
	v_rcp_f32_e32 v43, v43
	v_rcp_f32_e32 v42, v42
	s_nop 0
	v_pk_fma_f32 v[42:43], v[42:43], s[10:11], 0.5 op_sel_hi:[1,0,0]
	s_nop 0
	v_cvt_i32_f32_sdwa v42, v42 dst_sel:WORD_1 dst_unused:UNUSED_PAD src0_sel:DWORD
	v_cvt_i32_f32_sdwa v43, v43 dst_sel:WORD_1 dst_unused:UNUSED_PAD src0_sel:DWORD
	v_or_b32_e32 v45, v45, v42
	v_or_b32_e32 v44, v44, v43
	v_pk_add_f32 v[42:43], v[46:47], 1.0 op_sel_hi:[1,0]
	s_nop 0
	v_rcp_f32_e32 v43, v43
	v_rcp_f32_e32 v42, v42
	s_nop 0
	v_pk_fma_f32 v[42:43], v[42:43], s[10:11], 0.5 op_sel_hi:[1,0,0]
	s_nop 0
	v_cvt_i32_f32_sdwa v43, v43 dst_sel:BYTE_3 dst_unused:UNUSED_PAD src0_sel:DWORD
	v_cvt_i32_f32_sdwa v42, v42 dst_sel:BYTE_3 dst_unused:UNUSED_PAD src0_sel:DWORD
	v_or_b32_e32 v43, v44, v43
	v_exp_f32_e32 v44, v39
	v_mul_f32_e32 v39, v40, v52
	v_mul_f32_e32 v39, 0xbfb8aa3b, v39
	v_exp_f32_e32 v40, v39
	v_mul_f32_e32 v39, v41, v53
	v_mul_f32_e32 v39, 0xbfb8aa3b, v39
	v_exp_f32_e32 v46, v39
	v_exp_f32_e32 v39, v34
	v_mul_f32_e32 v34, v35, v51
	v_mul_f32_e32 v34, 0xbfb8aa3b, v34
	v_or_b32_e32 v42, v45, v42
	v_exp_f32_e32 v45, v34
	v_mul_f32_e32 v34, v36, v52
	v_mul_f32_e32 v34, 0xbfb8aa3b, v34
	v_exp_f32_e32 v41, v34
	v_mul_f32_e32 v34, v37, v53
	v_mul_f32_e32 v34, 0xbfb8aa3b, v34
	v_exp_f32_e32 v47, v34
	v_pk_add_f32 v[34:35], v[38:39], 1.0 op_sel_hi:[1,0]
	s_nop 0
	v_rcp_f32_e32 v35, v35
	v_rcp_f32_e32 v34, v34
	s_nop 0
	v_pk_fma_f32 v[34:35], v[34:35], s[10:11], 0.5 op_sel_hi:[1,0,0]
	s_nop 0
	v_cvt_i32_f32_e32 v36, v35
	v_cvt_i32_f32_e32 v37, v34
	v_pk_add_f32 v[34:35], v[44:45], 1.0 op_sel_hi:[1,0]
	s_nop 0
	v_rcp_f32_e32 v35, v35
	v_rcp_f32_e32 v34, v34
	s_nop 0
	v_pk_fma_f32 v[34:35], v[34:35], s[10:11], 0.5 op_sel_hi:[1,0,0]
	s_nop 0
	v_cvt_i32_f32_e32 v34, v34
	v_cvt_i32_f32_e32 v35, v35
	v_lshlrev_b32_e32 v34, 8, v34
	v_lshlrev_b32_e32 v35, 8, v35
	v_or_b32_e32 v36, v35, v36
	v_or_b32_e32 v37, v34, v37
	v_pk_add_f32 v[34:35], v[40:41], 1.0 op_sel_hi:[1,0]
	s_nop 0
	v_rcp_f32_e32 v35, v35
	v_rcp_f32_e32 v34, v34
	s_nop 0
	v_pk_fma_f32 v[34:35], v[34:35], s[10:11], 0.5 op_sel_hi:[1,0,0]
	s_nop 0
	v_cvt_i32_f32_sdwa v34, v34 dst_sel:WORD_1 dst_unused:UNUSED_PAD src0_sel:DWORD
	v_cvt_i32_f32_sdwa v35, v35 dst_sel:WORD_1 dst_unused:UNUSED_PAD src0_sel:DWORD
	v_or_b32_e32 v37, v37, v34
	v_or_b32_e32 v36, v36, v35
	v_pk_add_f32 v[34:35], v[46:47], 1.0 op_sel_hi:[1,0]
	s_nop 0
	v_rcp_f32_e32 v35, v35
	v_rcp_f32_e32 v34, v34
	s_nop 0
	v_pk_fma_f32 v[34:35], v[34:35], s[10:11], 0.5 op_sel_hi:[1,0,0]
	s_nop 0
	v_cvt_i32_f32_sdwa v34, v34 dst_sel:BYTE_3 dst_unused:UNUSED_PAD src0_sel:DWORD
	v_cvt_i32_f32_sdwa v35, v35 dst_sel:BYTE_3 dst_unused:UNUSED_PAD src0_sel:DWORD
	v_or_b32_e32 v44, v37, v34
	v_or_b32_e32 v45, v36, v35
	v_mov_b32_e32 v34, v80
	v_mov_b32_e32 v35, v81
	v_mov_b32_e32 v36, v82
	v_mov_b32_e32 v37, v83
	global_store_dwordx4 v0, v[42:45], s[0:1] offset:16
	s_waitcnt lgkmcnt(0)
; DI float sigmoidf_(float v) { return 1.f / (1.f + __expf(-v)); }
; DI void phaseA_tile(const P& p, int layer, int mt, int nt, char* lds) {
;     ...
;     for (int mi = 0; mi < 4; ++mi) {
;       unsigned wv[4];
; #pragma unroll
;       for (int ni = 0; ni < 4; ++ni) {
;         unsigned w_ = 0u;
; #pragma unroll
;         for (int j = 0; j < 4; ++j) {
;           const float r = rr[wm * 64 + mi * 16 + fq * 4 + j];
;           w_ |= ((unsigned)(int)(sigmoidf_(acc[mi][ni][j] * r) * 255.f + 0.5f)) << (8 * j);
;         }
;         wv[ni] = w_;
;       }
;       *(u32x4*)(G + mi * 4) = u32x4{wv[0], wv[1], wv[2], wv[3]};
	v_mul_f32_e32 v31, v31, v35
	v_mul_f32_e32 v31, 0xbfb8aa3b, v31
	v_exp_f32_e32 v38, v31
	v_mul_f32_e32 v31, v32, v36
	v_mul_f32_e32 v31, 0xbfb8aa3b, v31
	v_exp_f32_e32 v32, v31
	v_mul_f32_e32 v31, v33, v37
	v_mul_f32_e32 v26, v26, v34
	v_mul_f32_e32 v31, 0xbfb8aa3b, v31
	v_mul_f32_e32 v26, 0xbfb8aa3b, v26
	v_mul_f32_e32 v30, v30, v34
	v_exp_f32_e32 v40, v31
	v_exp_f32_e32 v31, v26
	v_mul_f32_e32 v26, v27, v35
	v_mul_f32_e32 v30, 0xbfb8aa3b, v30
	v_mul_f32_e32 v26, 0xbfb8aa3b, v26
	v_exp_f32_e32 v30, v30
	v_exp_f32_e32 v39, v26
	v_mul_f32_e32 v26, v28, v36
	v_mul_f32_e32 v26, 0xbfb8aa3b, v26
	v_exp_f32_e32 v33, v26
	v_mul_f32_e32 v26, v29, v37
	v_mul_f32_e32 v26, 0xbfb8aa3b, v26
	v_exp_f32_e32 v41, v26
	v_pk_add_f32 v[26:27], v[30:31], 1.0 op_sel_hi:[1,0]
	v_mul_f32_e32 v23, v23, v35
	v_mul_f32_e32 v23, 0xbfb8aa3b, v23
	v_mul_f32_e32 v18, v18, v34
	v_mul_f32_e32 v18, 0xbfb8aa3b, v18
	v_rcp_f32_e32 v27, v27
	v_mul_f32_e32 v22, v22, v34
	v_mul_f32_e32 v22, 0xbfb8aa3b, v22
	v_exp_f32_e32 v22, v22
	v_rcp_f32_e32 v26, v26
	s_nop 0
	v_pk_fma_f32 v[26:27], v[26:27], s[10:11], 0.5 op_sel_hi:[1,0,0]
	s_nop 0
	v_cvt_i32_f32_e32 v28, v27
	v_cvt_i32_f32_e32 v29, v26
	v_pk_add_f32 v[26:27], v[38:39], 1.0 op_sel_hi:[1,0]
	s_nop 0
	v_rcp_f32_e32 v27, v27
	v_rcp_f32_e32 v26, v26
	s_nop 0
	v_pk_fma_f32 v[26:27], v[26:27], s[10:11], 0.5 op_sel_hi:[1,0,0]
	s_nop 0
	v_cvt_i32_f32_e32 v26, v26
	v_cvt_i32_f32_e32 v27, v27
	v_lshlrev_b32_e32 v26, 8, v26
	v_lshlrev_b32_e32 v27, 8, v27
	v_or_b32_e32 v28, v27, v28
	v_or_b32_e32 v29, v26, v29
	v_pk_add_f32 v[26:27], v[32:33], 1.0 op_sel_hi:[1,0]
	s_nop 0
	v_rcp_f32_e32 v27, v27
	v_rcp_f32_e32 v26, v26
	s_nop 0
	v_pk_fma_f32 v[26:27], v[26:27], s[10:11], 0.5 op_sel_hi:[1,0,0]
	s_nop 0
	v_cvt_i32_f32_sdwa v26, v26 dst_sel:WORD_1 dst_unused:UNUSED_PAD src0_sel:DWORD
	v_cvt_i32_f32_sdwa v27, v27 dst_sel:WORD_1 dst_unused:UNUSED_PAD src0_sel:DWORD
	v_or_b32_e32 v29, v29, v26
	v_or_b32_e32 v28, v28, v27
	v_pk_add_f32 v[26:27], v[40:41], 1.0 op_sel_hi:[1,0]
	s_nop 0
	v_rcp_f32_e32 v27, v27
	v_rcp_f32_e32 v26, v26
	s_nop 0
	v_pk_fma_f32 v[26:27], v[26:27], s[10:11], 0.5 op_sel_hi:[1,0,0]
	s_nop 0
	v_cvt_i32_f32_sdwa v27, v27 dst_sel:BYTE_3 dst_unused:UNUSED_PAD src0_sel:DWORD
	v_cvt_i32_f32_sdwa v26, v26 dst_sel:BYTE_3 dst_unused:UNUSED_PAD src0_sel:DWORD
	v_or_b32_e32 v27, v28, v27
	v_exp_f32_e32 v28, v23
	v_mul_f32_e32 v23, v24, v36
	v_mul_f32_e32 v23, 0xbfb8aa3b, v23
	v_exp_f32_e32 v24, v23
	v_mul_f32_e32 v23, v25, v37
	v_mul_f32_e32 v23, 0xbfb8aa3b, v23
	v_exp_f32_e32 v30, v23
	v_exp_f32_e32 v23, v18
	v_mul_f32_e32 v18, v19, v35
	v_mul_f32_e32 v18, 0xbfb8aa3b, v18
	v_or_b32_e32 v26, v29, v26
	v_exp_f32_e32 v29, v18
	v_mul_f32_e32 v18, v20, v36
	v_mul_f32_e32 v18, 0xbfb8aa3b, v18
	v_exp_f32_e32 v25, v18
	v_mul_f32_e32 v18, v21, v37
	v_mul_f32_e32 v18, 0xbfb8aa3b, v18
	v_exp_f32_e32 v31, v18
	v_pk_add_f32 v[18:19], v[22:23], 1.0 op_sel_hi:[1,0]
	s_nop 0
	v_rcp_f32_e32 v19, v19
	v_rcp_f32_e32 v18, v18
	s_nop 0
	v_pk_fma_f32 v[18:19], v[18:19], s[10:11], 0.5 op_sel_hi:[1,0,0]
	s_nop 0
	v_cvt_i32_f32_e32 v20, v19
	v_cvt_i32_f32_e32 v21, v18
	v_pk_add_f32 v[18:19], v[28:29], 1.0 op_sel_hi:[1,0]
	s_nop 0
	v_rcp_f32_e32 v19, v19
	v_rcp_f32_e32 v18, v18
	s_nop 0
	v_pk_fma_f32 v[18:19], v[18:19], s[10:11], 0.5 op_sel_hi:[1,0,0]
	s_nop 0
	v_cvt_i32_f32_e32 v18, v18
	v_cvt_i32_f32_e32 v19, v19
	v_lshlrev_b32_e32 v18, 8, v18
	v_lshlrev_b32_e32 v19, 8, v19
	v_or_b32_e32 v20, v19, v20
	v_or_b32_e32 v21, v18, v21
	v_pk_add_f32 v[18:19], v[24:25], 1.0 op_sel_hi:[1,0]
	s_nop 0
	v_rcp_f32_e32 v19, v19
	v_rcp_f32_e32 v18, v18
	s_nop 0
	v_pk_fma_f32 v[18:19], v[18:19], s[10:11], 0.5 op_sel_hi:[1,0,0]
	s_nop 0
	v_cvt_i32_f32_sdwa v18, v18 dst_sel:WORD_1 dst_unused:UNUSED_PAD src0_sel:DWORD
	v_cvt_i32_f32_sdwa v19, v19 dst_sel:WORD_1 dst_unused:UNUSED_PAD src0_sel:DWORD
	v_or_b32_e32 v21, v21, v18
	v_or_b32_e32 v20, v20, v19
	v_pk_add_f32 v[18:19], v[30:31], 1.0 op_sel_hi:[1,0]
	s_nop 0
	v_rcp_f32_e32 v19, v19
	v_rcp_f32_e32 v18, v18
	s_nop 0
	v_pk_fma_f32 v[18:19], v[18:19], s[10:11], 0.5 op_sel_hi:[1,0,0]
	s_nop 0
	v_cvt_i32_f32_sdwa v18, v18 dst_sel:BYTE_3 dst_unused:UNUSED_PAD src0_sel:DWORD
	v_cvt_i32_f32_sdwa v19, v19 dst_sel:BYTE_3 dst_unused:UNUSED_PAD src0_sel:DWORD
	v_or_b32_e32 v28, v21, v18
	v_or_b32_e32 v29, v20, v19
	v_mov_b32_e32 v18, v84
	v_mov_b32_e32 v19, v85
	v_mov_b32_e32 v20, v86
	v_mov_b32_e32 v21, v87
	global_store_dwordx4 v0, v[26:29], s[0:1] offset:32
	s_waitcnt lgkmcnt(0)
; DI float sigmoidf_(float v) { return 1.f / (1.f + __expf(-v)); }
; DI void phaseA_tile(const P& p, int layer, int mt, int nt, char* lds) {
;     ...
;     for (int mi = 0; mi < 4; ++mi) {
;       unsigned wv[4];
; #pragma unroll
;       for (int ni = 0; ni < 4; ++ni) {
;         unsigned w_ = 0u;
; #pragma unroll
;         for (int j = 0; j < 4; ++j) {
;           const float r = rr[wm * 64 + mi * 16 + fq * 4 + j];
;           w_ |= ((unsigned)(int)(sigmoidf_(acc[mi][ni][j] * r) * 255.f + 0.5f)) << (8 * j);
;         }
;         wv[ni] = w_;
;       }
;       *(u32x4*)(G + mi * 4) = u32x4{wv[0], wv[1], wv[2], wv[3]};
;     }
;     return;
	v_mul_f32_e32 v14, v14, v18
	v_mul_f32_e32 v10, v10, v18
	v_mul_f32_e32 v14, 0xbfb8aa3b, v14
	v_mul_f32_e32 v10, 0xbfb8aa3b, v10
	v_exp_f32_e32 v22, v14
	v_mul_f32_e32 v14, v15, v19
	v_exp_f32_e32 v23, v10
	v_mul_f32_e32 v10, v11, v19
	v_mul_f32_e32 v14, 0xbfb8aa3b, v14
	v_mul_f32_e32 v10, 0xbfb8aa3b, v10
	v_exp_f32_e32 v24, v14
	v_mul_f32_e32 v14, v16, v20
	v_exp_f32_e32 v25, v10
	v_mul_f32_e32 v10, v12, v20
	v_mul_f32_e32 v14, 0xbfb8aa3b, v14
	v_mul_f32_e32 v10, 0xbfb8aa3b, v10
	v_exp_f32_e32 v16, v14
	v_mul_f32_e32 v14, v17, v21
	v_exp_f32_e32 v17, v10
	v_mul_f32_e32 v10, v13, v21
	v_mul_f32_e32 v10, 0xbfb8aa3b, v10
	v_exp_f32_e32 v15, v10
	v_pk_add_f32 v[10:11], v[22:23], 1.0 op_sel_hi:[1,0]
	v_mul_f32_e32 v14, 0xbfb8aa3b, v14
	v_exp_f32_e32 v14, v14
	v_mul_f32_e32 v6, v6, v18
	v_mul_f32_e32 v2, v2, v18
	v_rcp_f32_e32 v11, v11
	v_mul_f32_e32 v6, 0xbfb8aa3b, v6
	v_mul_f32_e32 v2, 0xbfb8aa3b, v2
	v_rcp_f32_e32 v10, v10
	s_nop 0
	v_pk_fma_f32 v[10:11], v[10:11], s[10:11], 0.5 op_sel_hi:[1,0,0]
	s_nop 0
	v_cvt_i32_f32_e32 v12, v11
	v_cvt_i32_f32_e32 v13, v10
	v_pk_add_f32 v[10:11], v[24:25], 1.0 op_sel_hi:[1,0]
	s_nop 0
	v_rcp_f32_e32 v11, v11
	v_rcp_f32_e32 v10, v10
	s_nop 0
	v_pk_fma_f32 v[10:11], v[10:11], s[10:11], 0.5 op_sel_hi:[1,0,0]
	s_nop 0
	v_cvt_i32_f32_e32 v10, v10
	v_cvt_i32_f32_e32 v11, v11
	v_lshlrev_b32_e32 v10, 8, v10
	v_lshlrev_b32_e32 v11, 8, v11
	v_or_b32_e32 v12, v11, v12
	v_or_b32_e32 v13, v10, v13
	v_pk_add_f32 v[10:11], v[16:17], 1.0 op_sel_hi:[1,0]
	s_nop 0
	v_rcp_f32_e32 v11, v11
	v_rcp_f32_e32 v10, v10
	s_nop 0
	v_pk_fma_f32 v[10:11], v[10:11], s[10:11], 0.5 op_sel_hi:[1,0,0]
	s_nop 0
	v_cvt_i32_f32_sdwa v10, v10 dst_sel:WORD_1 dst_unused:UNUSED_PAD src0_sel:DWORD
	v_cvt_i32_f32_sdwa v11, v11 dst_sel:WORD_1 dst_unused:UNUSED_PAD src0_sel:DWORD
	v_or_b32_e32 v13, v13, v10
	v_or_b32_e32 v12, v12, v11
	v_pk_add_f32 v[10:11], v[14:15], 1.0 op_sel_hi:[1,0]
	s_nop 0
	v_rcp_f32_e32 v11, v11
	v_rcp_f32_e32 v10, v10
	s_nop 0
	v_pk_fma_f32 v[10:11], v[10:11], s[10:11], 0.5 op_sel_hi:[1,0,0]
	s_nop 0
	v_cvt_i32_f32_sdwa v10, v10 dst_sel:BYTE_3 dst_unused:UNUSED_PAD src0_sel:DWORD
	v_cvt_i32_f32_sdwa v11, v11 dst_sel:BYTE_3 dst_unused:UNUSED_PAD src0_sel:DWORD
	v_or_b32_e32 v10, v13, v10
	v_or_b32_e32 v11, v12, v11
	v_exp_f32_e32 v12, v6
	v_mul_f32_e32 v6, v7, v19
	v_exp_f32_e32 v13, v2
	v_mul_f32_e32 v2, v3, v19
	v_mul_f32_e32 v6, 0xbfb8aa3b, v6
	v_mul_f32_e32 v2, 0xbfb8aa3b, v2
	v_exp_f32_e32 v14, v6
	v_mul_f32_e32 v6, v8, v20
	v_exp_f32_e32 v15, v2
	v_mul_f32_e32 v2, v4, v20
	v_mul_f32_e32 v6, 0xbfb8aa3b, v6
	v_mul_f32_e32 v2, 0xbfb8aa3b, v2
	v_exp_f32_e32 v8, v6
	v_mul_f32_e32 v6, v9, v21
	v_exp_f32_e32 v9, v2
	v_mul_f32_e32 v2, v5, v21
	v_mul_f32_e32 v2, 0xbfb8aa3b, v2
	v_exp_f32_e32 v7, v2
	v_pk_add_f32 v[2:3], v[12:13], 1.0 op_sel_hi:[1,0]
	v_mul_f32_e32 v6, 0xbfb8aa3b, v6
	v_exp_f32_e32 v6, v6
	v_rcp_f32_e32 v3, v3
	v_rcp_f32_e32 v2, v2
	s_nop 0
	v_pk_fma_f32 v[2:3], v[2:3], s[10:11], 0.5 op_sel_hi:[1,0,0]
	s_nop 0
	v_cvt_i32_f32_e32 v4, v3
	v_cvt_i32_f32_e32 v5, v2
	v_pk_add_f32 v[2:3], v[14:15], 1.0 op_sel_hi:[1,0]
	s_nop 0
	v_rcp_f32_e32 v3, v3
	v_rcp_f32_e32 v2, v2
	s_nop 0
	v_pk_fma_f32 v[2:3], v[2:3], s[10:11], 0.5 op_sel_hi:[1,0,0]
	s_nop 0
	v_cvt_i32_f32_e32 v2, v2
	v_cvt_i32_f32_e32 v3, v3
	v_lshlrev_b32_e32 v2, 8, v2
	v_lshlrev_b32_e32 v3, 8, v3
	v_or_b32_e32 v4, v3, v4
	v_or_b32_e32 v5, v2, v5
	v_pk_add_f32 v[2:3], v[8:9], 1.0 op_sel_hi:[1,0]
	s_nop 0
	v_rcp_f32_e32 v3, v3
	v_rcp_f32_e32 v2, v2
	s_nop 0
	v_pk_fma_f32 v[2:3], v[2:3], s[10:11], 0.5 op_sel_hi:[1,0,0]
	s_nop 0
	v_cvt_i32_f32_sdwa v2, v2 dst_sel:WORD_1 dst_unused:UNUSED_PAD src0_sel:DWORD
	v_cvt_i32_f32_sdwa v3, v3 dst_sel:WORD_1 dst_unused:UNUSED_PAD src0_sel:DWORD
	v_or_b32_e32 v5, v5, v2
	v_or_b32_e32 v4, v4, v3
	v_pk_add_f32 v[2:3], v[6:7], 1.0 op_sel_hi:[1,0]
	s_nop 0
	v_rcp_f32_e32 v3, v3
	s_movk_i32 s5, 0x2000
	v_rcp_f32_e32 v2, v2
	s_nop 0
	v_pk_fma_f32 v[2:3], v[2:3], s[10:11], 0.5 op_sel_hi:[1,0,0]
	s_nop 0
	v_cvt_i32_f32_sdwa v2, v2 dst_sel:BYTE_3 dst_unused:UNUSED_PAD src0_sel:DWORD
	v_cvt_i32_f32_sdwa v3, v3 dst_sel:BYTE_3 dst_unused:UNUSED_PAD src0_sel:DWORD
	v_or_b32_e32 v12, v5, v2
	v_or_b32_e32 v13, v4, v3
	global_store_dwordx4 v0, v[10:13], s[0:1] offset:48
	s_branch .LBB0_1183

; DI unsigned xb_ld(unsigned* p) { return __hip_atomic_load(p, __ATOMIC_RELAXED, __HIP_MEMORY_SCOPE_AGENT); }
; DI unsigned xb_add(unsigned* p, unsigned v) { return __hip_atomic_fetch_add(p, v, __ATOMIC_RELAXED, __HIP_MEMORY_SCOPE_AGENT); }
; #define XB_SPIN(cond, bar) do { unsigned _sp = 0; while (cond) { __builtin_amdgcn_s_sleep(1); \
;     if ((++_sp & 255u) == 0u) { if (xb_ld(&(bar)[XB_TMO])) break; if (_sp > XB_SPIN_CAP) { atomicAdd(&(bar)[XB_TMO], 1u); break; } } } } while (0)
; DI void xcd_barrier(const XcdBarrier& b) {
;     ...
;     if (old + 1u == (gen + 1u) * nloc) {
;       __builtin_amdgcn_fence(__ATOMIC_RELEASE, "agent");
;       asm volatile("s_waitcnt vmcnt(0)" ::: "memory");
;       const unsigned og = xb_add(&bar[XB_TOP], 1u);
;       const unsigned tg = og / nx;
;       if (og + 1u == (tg + 1u) * nx) xb_add(&bar[XB_TOPGEN], 1u);
;       else XB_SPIN(xb_ld(&bar[XB_TOPGEN]) == tg, bar);
;       __builtin_amdgcn_fence(__ATOMIC_ACQUIRE, "agent");
;       xb_add(&bar[XB_XGEN(b.x)], 1u);
;       asm volatile("s_waitcnt vmcnt(0)" ::: "memory");
;     } else {
.LBB0_2104:
	s_andn2_saveexec_b64 s[4:5], s[4:5]
	s_cbranch_execnz .LBB0_2105
.Lto11:
	s_getpc_b64 s[98:99]

; DI unsigned xb_ld(unsigned* p) { return __hip_atomic_load(p, __ATOMIC_RELAXED, __HIP_MEMORY_SCOPE_AGENT); }
; DI unsigned xb_add(unsigned* p, unsigned v) { return __hip_atomic_fetch_add(p, v, __ATOMIC_RELAXED, __HIP_MEMORY_SCOPE_AGENT); }
; #define XB_SPIN(cond, bar) do { unsigned _sp = 0; while (cond) { __builtin_amdgcn_s_sleep(1); \
;     if ((++_sp & 255u) == 0u) { if (xb_ld(&(bar)[XB_TMO])) break; if (_sp > XB_SPIN_CAP) { atomicAdd(&(bar)[XB_TMO], 1u); break; } } } } while (0)
; DI void xcd_barrier(const XcdBarrier& b) {
;     ...
;     if (old + 1u == (gen + 1u) * nloc) {
;       __builtin_amdgcn_fence(__ATOMIC_RELEASE, "agent");
;       asm volatile("s_waitcnt vmcnt(0)" ::: "memory");
;       const unsigned og = xb_add(&bar[XB_TOP], 1u);
;       const unsigned tg = og / nx;
;       if (og + 1u == (tg + 1u) * nx) xb_add(&bar[XB_TOPGEN], 1u);
;       else XB_SPIN(xb_ld(&bar[XB_TOPGEN]) == tg, bar);
;       __builtin_amdgcn_fence(__ATOMIC_ACQUIRE, "agent");
;       xb_add(&bar[XB_XGEN(b.x)], 1u);
;       asm volatile("s_waitcnt vmcnt(0)" ::: "memory");
.LBB0_2105:
	s_mov_b64 s[4:5], exec
	buffer_wbl2 sc1
	s_waitcnt lgkmcnt(0)
	s_waitcnt vmcnt(0)
	buffer_inv sc1
	v_readlane_b32 s6, v238, 21
	v_readlane_b32 s7, v238, 22
	v_mov_b32_e32 v3, 1
	s_nop 3
	global_atomic_add v3, v1, v3, s[6:7] sc0
	v_add_u32_e32 v5, 1, v0
	v_mul_lo_u32 v5, v5, v2
	v_readlane_b32 s6, v238, 23
	v_readlane_b32 s7, v238, 24
	s_waitcnt vmcnt(0)
	v_add_u32_e32 v3, 1, v3
	v_cmp_eq_u32_e32 vcc, v3, v5
	s_mov_b32 s8, 0
	s_cbranch_vccnz .Lld_last
.Lld_spin:
	global_load_dword v4, v1, s[6:7] sc1
	s_waitcnt vmcnt(0)
	v_cmp_ne_u32_e32 vcc, v4, v0
	s_cbranch_vccnz .Lto11
	s_sleep 1
	s_add_i32 s8, s8, 1
	s_cmp_lt_u32 s8, 0x400000
	s_cbranch_scc1 .Lld_spin
	s_branch .Lto11
.Lld_last:
	global_atomic_add v1, v165, s[6:7]
	v_readlane_b32 s12, v240, 22
	v_readlane_b32 s13, v240, 23
	v_mov_b32_e32 v4, 0x2400
	s_nop 3
	global_atomic_add v4, v165, s[12:13]
	v_add_u32_e32 v4, 0x100, v4
	global_atomic_add v4, v165, s[12:13]
	v_add_u32_e32 v4, 0x100, v4
	global_atomic_add v4, v165, s[12:13]
	v_add_u32_e32 v4, 0x100, v4
	global_atomic_add v4, v165, s[12:13]
	v_add_u32_e32 v4, 0x100, v4
	global_atomic_add v4, v165, s[12:13]
	v_add_u32_e32 v4, 0x100, v4
	global_atomic_add v4, v165, s[12:13]
	v_add_u32_e32 v4, 0x100, v4
	global_atomic_add v4, v165, s[12:13]
	v_add_u32_e32 v4, 0x100, v4
	global_atomic_add v4, v165, s[12:13]
	v_add_u32_e32 v4, 0x100, v4
	global_atomic_add v4, v165, s[12:13]
	v_add_u32_e32 v4, 0x100, v4
	global_atomic_add v4, v165, s[12:13]
	v_add_u32_e32 v4, 0x100, v4
	global_atomic_add v4, v165, s[12:13]
	v_add_u32_e32 v4, 0x100, v4
	global_atomic_add v4, v165, s[12:13]
	v_add_u32_e32 v4, 0x100, v4
	global_atomic_add v4, v165, s[12:13]
	v_add_u32_e32 v4, 0x100, v4
	global_atomic_add v4, v165, s[12:13]
	v_add_u32_e32 v4, 0x100, v4
	global_atomic_add v4, v165, s[12:13]
	v_add_u32_e32 v4, 0x100, v4
	global_atomic_add v4, v165, s[12:13]
	s_branch .Lto11
